# in-projection wide mainloops: each LDS-DMA load issued in the shadow of an MFMA instead of before the fragment reads
# speedup vs baseline: 1.0090x; 1.0090x over previous
.Lp2a_bar:
	s_barrier
	v_add_u32_e32 v137, s5, v133
	v_add_u32_e32 v138, s5, v134
	v_add_u32_e32 v139, s5, v135
	v_add_u32_e32 v140, s5, v136
	s_cmp_gt_u32 s4, 29
	s_cbranch_scc1 .Lp2a_plain
	s_add_u32 vcc_hi, s5, 0xc000
	s_sub_u32 m0, vcc_hi, 0x12000
	s_cmp_lt_u32 s5, 0x6000
	s_cselect_b32 vcc_hi, vcc_hi, m0
	s_add_u32 m0, vcc_hi, vcc_lo
	ds_read_b128 v[214:217], v139
	ds_read_b128 v[218:221], v137
	ds_read_b128 v[222:225], v138
	ds_read_b128 v[226:229], v140
	ds_read_b128 v[230:233], v137 offset:2048
	ds_read_b128 v[234:237], v138 offset:2048
	s_waitcnt lgkmcnt(4)
	v_mfma_f32_32x32x16_bf16 v[112:127], v[214:217], v[218:221], v[112:127]
	s_nop 0
	global_load_lds_dwordx4 v128, s[0:1]
	s_waitcnt lgkmcnt(1)
	v_mfma_f32_32x32x16_bf16 v[48:63], v[214:217], v[230:233], v[48:63]
	s_add_u32 m0, m0, 0x1000
	s_nop 0
	global_load_lds_dwordx4 v129, s[0:1]
	ds_read_b128 v[214:217], v139 offset:2048
	ds_read_b128 v[238:241], v140 offset:2048
	s_waitcnt lgkmcnt(1)
	v_mfma_f32_32x32x16_bf16 v[96:111], v[214:217], v[218:221], v[96:111]
	s_add_u32 m0, m0, 0x1000
	s_nop 0
	global_load_lds_dwordx4 v128, s[6:7]
	v_mfma_f32_32x32x16_bf16 v[32:47], v[214:217], v[230:233], v[32:47]
	s_add_u32 m0, m0, 0x1000
	s_nop 0
	global_load_lds_dwordx4 v129, s[6:7]
	ds_read_b128 v[214:217], v139 offset:4096
	ds_read_b128 v[242:245], v140 offset:4096
	s_waitcnt lgkmcnt(1)
	v_mfma_f32_32x32x16_bf16 v[80:95], v[214:217], v[218:221], v[80:95]
	s_add_u32 m0, m0, 0x1000
	s_nop 0
	global_load_lds_dwordx4 v130, s[6:7]
	v_mfma_f32_32x32x16_bf16 v[16:31], v[214:217], v[230:233], v[16:31]
	s_add_u32 m0, m0, 0x1000
	s_nop 0
	global_load_lds_dwordx4 v131, s[6:7]
	s_add_u32 s0, s0, 64
	s_addc_u32 s1, s1, 0
	s_add_u32 s6, s6, 64
	s_addc_u32 s7, s7, 0
	ds_read_b128 v[214:217], v139 offset:6144
	ds_read_b128 v[246:249], v140 offset:6144
	s_waitcnt lgkmcnt(1)
	v_mfma_f32_32x32x16_bf16 v[64:79], v[214:217], v[218:221], v[64:79]
	v_mfma_f32_32x32x16_bf16 v[0:15], v[214:217], v[230:233], v[0:15]
	v_mfma_f32_32x32x16_bf16 v[112:127], v[226:229], v[222:225], v[112:127]
	v_mfma_f32_32x32x16_bf16 v[48:63], v[226:229], v[234:237], v[48:63]
	v_mfma_f32_32x32x16_bf16 v[96:111], v[238:241], v[222:225], v[96:111]
	v_mfma_f32_32x32x16_bf16 v[32:47], v[238:241], v[234:237], v[32:47]
	v_mfma_f32_32x32x16_bf16 v[80:95], v[242:245], v[222:225], v[80:95]
	v_mfma_f32_32x32x16_bf16 v[16:31], v[242:245], v[234:237], v[16:31]
	s_waitcnt lgkmcnt(0)
	v_mfma_f32_32x32x16_bf16 v[64:79], v[246:249], v[222:225], v[64:79]
	v_mfma_f32_32x32x16_bf16 v[0:15], v[246:249], v[234:237], v[0:15]
	s_branch .Lp2a_adv
.Lp2a_plain:
	ds_read_b128 v[214:217], v139
	ds_read_b128 v[218:221], v137
	ds_read_b128 v[222:225], v138
	ds_read_b128 v[226:229], v140
	ds_read_b128 v[230:233], v137 offset:2048
	ds_read_b128 v[234:237], v138 offset:2048
	s_waitcnt lgkmcnt(4)
	v_mfma_f32_32x32x16_bf16 v[112:127], v[214:217], v[218:221], v[112:127]
	s_waitcnt lgkmcnt(1)
	v_mfma_f32_32x32x16_bf16 v[48:63], v[214:217], v[230:233], v[48:63]
	ds_read_b128 v[214:217], v139 offset:2048
	ds_read_b128 v[238:241], v140 offset:2048
	s_waitcnt lgkmcnt(1)
	v_mfma_f32_32x32x16_bf16 v[96:111], v[214:217], v[218:221], v[96:111]
	v_mfma_f32_32x32x16_bf16 v[32:47], v[214:217], v[230:233], v[32:47]
	ds_read_b128 v[214:217], v139 offset:4096
	ds_read_b128 v[242:245], v140 offset:4096
	s_waitcnt lgkmcnt(1)
	v_mfma_f32_32x32x16_bf16 v[80:95], v[214:217], v[218:221], v[80:95]
	v_mfma_f32_32x32x16_bf16 v[16:31], v[214:217], v[230:233], v[16:31]
	ds_read_b128 v[214:217], v139 offset:6144
	ds_read_b128 v[246:249], v140 offset:6144
	s_waitcnt lgkmcnt(1)
	v_mfma_f32_32x32x16_bf16 v[64:79], v[214:217], v[218:221], v[64:79]
	v_mfma_f32_32x32x16_bf16 v[0:15], v[214:217], v[230:233], v[0:15]
	v_mfma_f32_32x32x16_bf16 v[112:127], v[226:229], v[222:225], v[112:127]
	v_mfma_f32_32x32x16_bf16 v[48:63], v[226:229], v[234:237], v[48:63]
	v_mfma_f32_32x32x16_bf16 v[96:111], v[238:241], v[222:225], v[96:111]
	v_mfma_f32_32x32x16_bf16 v[32:47], v[238:241], v[234:237], v[32:47]
	v_mfma_f32_32x32x16_bf16 v[80:95], v[242:245], v[222:225], v[80:95]
	v_mfma_f32_32x32x16_bf16 v[16:31], v[242:245], v[234:237], v[16:31]
	s_waitcnt lgkmcnt(0)
	v_mfma_f32_32x32x16_bf16 v[64:79], v[246:249], v[222:225], v[64:79]
	v_mfma_f32_32x32x16_bf16 v[0:15], v[246:249], v[234:237], v[0:15]
.Lp2a_adv:
	s_add_u32 s5, s5, 0x6000
	s_cmp_eq_u32 s5, 0x12000
	s_cselect_b32 s5, 0, s5
	s_add_i32 s4, s4, 1
	s_cmp_lg_u32 s4, 32
	s_cbranch_scc1 .Lp2a_top
	s_barrier

.Lp2b_bar:
	s_barrier
	v_add_u32_e32 v137, s5, v133
	v_add_u32_e32 v138, s5, v134
	v_add_u32_e32 v139, s5, v135
	v_add_u32_e32 v140, s5, v136
	s_cmp_gt_u32 s4, 29
	s_cbranch_scc1 .Lp2b_plain
	s_add_u32 vcc_hi, s5, 0xc000
	s_sub_u32 m0, vcc_hi, 0x12000
	s_cmp_lt_u32 s5, 0x6000
	s_cselect_b32 vcc_hi, vcc_hi, m0
	s_add_u32 m0, vcc_hi, vcc_lo
	ds_read_b128 v[174:177], v137
	ds_read_b128 v[214:217], v139
	ds_read_b128 v[218:221], v138
	ds_read_b128 v[222:225], v140
	ds_read_b128 v[226:229], v137 offset:2048
	ds_read_b128 v[230:233], v138 offset:2048
	s_waitcnt lgkmcnt(1)
	v_mfma_f32_32x32x16_bf16 v[48:63], v[226:229], v[214:217], v[48:63]
	s_nop 0
	global_load_lds_dwordx4 v128, s[0:1]
	v_mfma_f32_32x32x16_bf16 v[112:127], v[174:177], v[214:217], v[112:127]
	s_add_u32 m0, m0, 0x1000
	s_nop 0
	global_load_lds_dwordx4 v129, s[0:1]
	ds_read_b128 v[214:217], v139 offset:2048
	ds_read_b128 v[234:237], v140 offset:2048
	s_waitcnt lgkmcnt(1)
	v_mfma_f32_32x32x16_bf16 v[96:111], v[174:177], v[214:217], v[96:111]
	s_add_u32 m0, m0, 0x1000
	s_nop 0
	global_load_lds_dwordx4 v128, s[6:7]
	v_mfma_f32_32x32x16_bf16 v[32:47], v[226:229], v[214:217], v[32:47]
	s_add_u32 m0, m0, 0x1000
	s_nop 0
	global_load_lds_dwordx4 v129, s[6:7]
	ds_read_b128 v[214:217], v139 offset:4096
	ds_read_b128 v[238:241], v140 offset:4096
	s_waitcnt lgkmcnt(1)
	v_mfma_f32_32x32x16_bf16 v[80:95], v[174:177], v[214:217], v[80:95]
	s_add_u32 m0, m0, 0x1000
	s_nop 0
	global_load_lds_dwordx4 v130, s[6:7]
	v_mfma_f32_32x32x16_bf16 v[16:31], v[226:229], v[214:217], v[16:31]
	s_add_u32 m0, m0, 0x1000
	s_nop 0
	global_load_lds_dwordx4 v131, s[6:7]
	s_add_u32 s0, s0, 64
	s_addc_u32 s1, s1, 0
	s_add_u32 s6, s6, 64
	s_addc_u32 s7, s7, 0
	ds_read_b128 v[214:217], v139 offset:6144
	ds_read_b128 v[242:245], v140 offset:6144
	s_waitcnt lgkmcnt(1)
	v_mfma_f32_32x32x16_bf16 v[64:79], v[174:177], v[214:217], v[64:79]
	v_mfma_f32_32x32x16_bf16 v[0:15], v[226:229], v[214:217], v[0:15]
	v_mfma_f32_32x32x16_bf16 v[112:127], v[218:221], v[222:225], v[112:127]
	v_mfma_f32_32x32x16_bf16 v[48:63], v[230:233], v[222:225], v[48:63]
	v_mfma_f32_32x32x16_bf16 v[96:111], v[218:221], v[234:237], v[96:111]
	v_mfma_f32_32x32x16_bf16 v[32:47], v[230:233], v[234:237], v[32:47]
	v_mfma_f32_32x32x16_bf16 v[80:95], v[218:221], v[238:241], v[80:95]
	v_mfma_f32_32x32x16_bf16 v[16:31], v[230:233], v[238:241], v[16:31]
	s_waitcnt lgkmcnt(0)
	v_mfma_f32_32x32x16_bf16 v[64:79], v[218:221], v[242:245], v[64:79]
	v_mfma_f32_32x32x16_bf16 v[0:15], v[230:233], v[242:245], v[0:15]
	s_branch .Lp2b_adv
.Lp2b_plain:
	ds_read_b128 v[174:177], v137
	ds_read_b128 v[214:217], v139
	ds_read_b128 v[218:221], v138
	ds_read_b128 v[222:225], v140
	ds_read_b128 v[226:229], v137 offset:2048
	ds_read_b128 v[230:233], v138 offset:2048
	s_waitcnt lgkmcnt(1)
	v_mfma_f32_32x32x16_bf16 v[48:63], v[226:229], v[214:217], v[48:63]
	v_mfma_f32_32x32x16_bf16 v[112:127], v[174:177], v[214:217], v[112:127]
	ds_read_b128 v[214:217], v139 offset:2048
	ds_read_b128 v[234:237], v140 offset:2048
	s_waitcnt lgkmcnt(1)
	v_mfma_f32_32x32x16_bf16 v[96:111], v[174:177], v[214:217], v[96:111]
	v_mfma_f32_32x32x16_bf16 v[32:47], v[226:229], v[214:217], v[32:47]
	ds_read_b128 v[214:217], v139 offset:4096
	ds_read_b128 v[238:241], v140 offset:4096
	s_waitcnt lgkmcnt(1)
	v_mfma_f32_32x32x16_bf16 v[80:95], v[174:177], v[214:217], v[80:95]
	v_mfma_f32_32x32x16_bf16 v[16:31], v[226:229], v[214:217], v[16:31]
	ds_read_b128 v[214:217], v139 offset:6144
	ds_read_b128 v[242:245], v140 offset:6144
	s_waitcnt lgkmcnt(1)
	v_mfma_f32_32x32x16_bf16 v[64:79], v[174:177], v[214:217], v[64:79]
	v_mfma_f32_32x32x16_bf16 v[0:15], v[226:229], v[214:217], v[0:15]
	v_mfma_f32_32x32x16_bf16 v[112:127], v[218:221], v[222:225], v[112:127]
	v_mfma_f32_32x32x16_bf16 v[48:63], v[230:233], v[222:225], v[48:63]
	v_mfma_f32_32x32x16_bf16 v[96:111], v[218:221], v[234:237], v[96:111]
	v_mfma_f32_32x32x16_bf16 v[32:47], v[230:233], v[234:237], v[32:47]
	v_mfma_f32_32x32x16_bf16 v[80:95], v[218:221], v[238:241], v[80:95]
	v_mfma_f32_32x32x16_bf16 v[16:31], v[230:233], v[238:241], v[16:31]
	s_waitcnt lgkmcnt(0)
	v_mfma_f32_32x32x16_bf16 v[64:79], v[218:221], v[242:245], v[64:79]
	v_mfma_f32_32x32x16_bf16 v[0:15], v[230:233], v[242:245], v[0:15]
